# scalar-base K-loop DMA addressing + relax flag taken from the scalar mask + sub-phase 3/4 waits behind their MMA block + redundant m0 padding nops dropped (all ten GEMM K-loops); on top of non-scaled
# speedup vs baseline: 1.0126x; 1.0044x over previous
.LBB0_250:
	s_waitcnt lgkmcnt(0)
	s_barrier
	s_setprio 1
	s_waitcnt lgkmcnt(0)
	v_mfma_f32_16x16x128_f8f6f4 v[126:129], v[26:33], v[58:65], v[126:129]
	v_mfma_f32_16x16x128_f8f6f4 v[122:125], v[18:25], v[58:65], v[122:125]
	v_mfma_f32_16x16x128_f8f6f4 v[110:113], v[26:33], v[50:57], v[110:113]
	v_mfma_f32_16x16x128_f8f6f4 v[106:109], v[18:25], v[50:57], v[106:109]
	v_mfma_f32_16x16x128_f8f6f4 v[94:97], v[26:33], v[42:49], v[94:97]
	v_mfma_f32_16x16x128_f8f6f4 v[90:93], v[18:25], v[42:49], v[90:93]
	v_mfma_f32_16x16x128_f8f6f4 v[78:81], v[26:33], v[34:41], v[78:81]
	v_mfma_f32_16x16x128_f8f6f4 v[74:77], v[18:25], v[34:41], v[74:77]
	s_setprio 0
	s_setprio 1
	v_mfma_f32_16x16x128_f8f6f4 v[118:121], v[10:17], v[58:65], v[118:121]
	v_mfma_f32_16x16x128_f8f6f4 v[114:117], v[2:9], v[58:65], v[114:117]
	v_mfma_f32_16x16x128_f8f6f4 v[102:105], v[10:17], v[50:57], v[102:105]
	v_mfma_f32_16x16x128_f8f6f4 v[98:101], v[2:9], v[50:57], v[98:101]
	v_mfma_f32_16x16x128_f8f6f4 v[86:89], v[10:17], v[42:49], v[86:89]
	v_mfma_f32_16x16x128_f8f6f4 v[82:85], v[2:9], v[42:49], v[82:85]
	v_mfma_f32_16x16x128_f8f6f4 v[70:73], v[10:17], v[34:41], v[70:73]
	v_mfma_f32_16x16x128_f8f6f4 v[66:69], v[2:9], v[34:41], v[66:69]
	s_setprio 0
	s_barrier
	v_add_u32_e32 v14, s53, v205
	v_add_u32_e32 v30, s58, v205
	ds_read_b128 v[2:5], v14
	ds_read_b128 v[6:9], v14 offset:1024
	ds_read_b128 v[10:13], v14 offset:2048
	ds_read_b128 v[14:17], v14 offset:3072
	ds_read_b128 v[18:21], v30
	ds_read_b128 v[22:25], v30 offset:1024
	ds_read_b128 v[26:29], v30 offset:2048
	ds_read_b128 v[30:33], v30 offset:3072
	s_add_u32 s100, s36, 0x530000
	s_addc_u32 s101, s37, 0
	s_mov_b32 m0, s51
	ds_read_b128 v[34:37], v234 offset:32768
	ds_read_b128 v[38:41], v234 offset:33792
	ds_read_b128 v[42:45], v234 offset:34816
	ds_read_b128 v[46:49], v234 offset:35840
	ds_read_b128 v[50:53], v234 offset:36864
	ds_read_b128 v[54:57], v234 offset:37888
	ds_read_b128 v[58:61], v234 offset:38912
	ds_read_b128 v[62:65], v234 offset:39936
	global_load_lds_dwordx4 v194, s[100:101]
	s_mov_b32 m0, s52
	s_nop 0
	global_load_lds_dwordx4 v198, s[100:101]
	s_waitcnt lgkmcnt(0)
	s_barrier
	s_setprio 1
	s_waitcnt lgkmcnt(0)
	v_mfma_f32_16x16x128_f8f6f4 v[190:193], v[2:9], v[34:41], v[190:193]
	v_mfma_f32_16x16x128_f8f6f4 v[186:189], v[10:17], v[34:41], v[186:189]
	v_mfma_f32_16x16x128_f8f6f4 v[174:177], v[2:9], v[42:49], v[174:177]
	v_mfma_f32_16x16x128_f8f6f4 v[170:173], v[10:17], v[42:49], v[170:173]
	v_mfma_f32_16x16x128_f8f6f4 v[158:161], v[2:9], v[50:57], v[158:161]
	v_mfma_f32_16x16x128_f8f6f4 v[154:157], v[10:17], v[50:57], v[154:157]
	v_mfma_f32_16x16x128_f8f6f4 v[142:145], v[2:9], v[58:65], v[142:145]
	v_mfma_f32_16x16x128_f8f6f4 v[138:141], v[10:17], v[58:65], v[138:141]
	s_setprio 0
	s_setprio 1
	v_mfma_f32_16x16x128_f8f6f4 v[182:185], v[18:25], v[34:41], v[182:185]
	v_mfma_f32_16x16x128_f8f6f4 v[178:181], v[26:33], v[34:41], v[178:181]
	v_mfma_f32_16x16x128_f8f6f4 v[166:169], v[18:25], v[42:49], v[166:169]
	v_mfma_f32_16x16x128_f8f6f4 v[162:165], v[26:33], v[42:49], v[162:165]
	v_mfma_f32_16x16x128_f8f6f4 v[150:153], v[18:25], v[50:57], v[150:153]
	v_mfma_f32_16x16x128_f8f6f4 v[146:149], v[26:33], v[50:57], v[146:149]
	v_mfma_f32_16x16x128_f8f6f4 v[134:137], v[18:25], v[58:65], v[134:137]
	v_mfma_f32_16x16x128_f8f6f4 v[130:133], v[26:33], v[58:65], v[130:133]
	s_setprio 0
	s_waitcnt vmcnt(8)
	s_barrier
	s_mov_b32 m0, s54
	ds_read_b128 v[34:37], v234 offset:49152
	ds_read_b128 v[38:41], v234 offset:50176
	ds_read_b128 v[42:45], v234 offset:51200
	ds_read_b128 v[46:49], v234 offset:52224
	ds_read_b128 v[50:53], v234 offset:53248
	ds_read_b128 v[54:57], v234 offset:54272
	ds_read_b128 v[58:61], v234 offset:55296
	ds_read_b128 v[62:65], v234 offset:56320
	s_add_u32 s98, s34, 0x80
	s_addc_u32 s99, s35, 0
	global_load_lds_dwordx4 v196, s[98:99]
	s_mov_b32 m0, s55
	s_nop 0
	global_load_lds_dwordx4 v200, s[98:99]
	s_mov_b32 m0, s59
	s_add_u32 s100, s82, 0x80
	s_addc_u32 s101, s83, 0
	global_load_lds_dwordx4 v196, s[100:101]
	s_mov_b32 m0, s60
	s_nop 0
	global_load_lds_dwordx4 v200, s[100:101]
	s_mov_b32 m0, s56
	s_add_u32 s98, s36, 0x80
	s_addc_u32 s99, s37, 0
	global_load_lds_dwordx4 v194, s[98:99]
	s_mov_b32 m0, s57
	s_nop 0
	global_load_lds_dwordx4 v198, s[98:99]
	s_waitcnt lgkmcnt(0)
	s_barrier
	s_setprio 1
	s_waitcnt lgkmcnt(0)
	v_mfma_f32_16x16x128_f8f6f4 v[126:129], v[2:9], v[34:41], v[126:129]
	v_mfma_f32_16x16x128_f8f6f4 v[122:125], v[10:17], v[34:41], v[122:125]
	v_mfma_f32_16x16x128_f8f6f4 v[110:113], v[2:9], v[42:49], v[110:113]
	v_mfma_f32_16x16x128_f8f6f4 v[106:109], v[10:17], v[42:49], v[106:109]
	v_mfma_f32_16x16x128_f8f6f4 v[94:97], v[2:9], v[50:57], v[94:97]
	v_mfma_f32_16x16x128_f8f6f4 v[90:93], v[10:17], v[50:57], v[90:93]
	v_mfma_f32_16x16x128_f8f6f4 v[78:81], v[2:9], v[58:65], v[78:81]
	v_mfma_f32_16x16x128_f8f6f4 v[74:77], v[10:17], v[58:65], v[74:77]
	s_setprio 0
	s_setprio 1
	v_mfma_f32_16x16x128_f8f6f4 v[118:121], v[18:25], v[34:41], v[118:121]
	v_mfma_f32_16x16x128_f8f6f4 v[114:117], v[26:33], v[34:41], v[114:117]
	v_mfma_f32_16x16x128_f8f6f4 v[102:105], v[18:25], v[42:49], v[102:105]
	v_mfma_f32_16x16x128_f8f6f4 v[98:101], v[26:33], v[42:49], v[98:101]
	v_mfma_f32_16x16x128_f8f6f4 v[86:89], v[18:25], v[50:57], v[86:89]
	v_mfma_f32_16x16x128_f8f6f4 v[82:85], v[26:33], v[50:57], v[82:85]
	v_mfma_f32_16x16x128_f8f6f4 v[70:73], v[18:25], v[58:65], v[70:73]
	v_mfma_f32_16x16x128_f8f6f4 v[66:69], v[26:33], v[58:65], v[66:69]
	s_setprio 0
	s_waitcnt vmcnt(8)
	s_barrier
	s_add_i32 s80, s80, 2
	s_add_u32 s30, s30, 0x100
	s_addc_u32 s31, s31, 0
	s_cmp_gt_u32 s80, 13
	s_cbranch_scc1 .LBB0_258
.LBB0_251:
	s_cmp_eq_u32 s30, 0
	s_cselect_b64 s[34:35], -1, 0
	s_and_b64 s[34:35], s[0:1], s[34:35]
	s_and_b32 s34, s34, 1
	ds_read_b128 v[26:29], v232
	ds_read_b128 v[30:33], v232 offset:1024
	ds_read_b128 v[18:21], v232 offset:2048
	ds_read_b128 v[22:25], v232 offset:3072
	ds_read_b128 v[10:13], v233
	ds_read_b128 v[14:17], v233 offset:1024
	ds_read_b128 v[2:5], v233 offset:2048
	ds_read_b128 v[6:9], v233 offset:3072
	s_add_u32 s98, s6, s30
	s_addc_u32 s99, s7, s31
	s_add_i32 m0, s49, 0xc000
	ds_read_b128 v[58:61], v234
	ds_read_b128 v[62:65], v234 offset:1024
	ds_read_b128 v[50:53], v234 offset:2048
	ds_read_b128 v[54:57], v234 offset:3072
	ds_read_b128 v[42:45], v234 offset:4096
	ds_read_b128 v[46:49], v234 offset:5120
	ds_read_b128 v[34:37], v234 offset:6144
	ds_read_b128 v[38:41], v234 offset:7168
	global_load_lds_dwordx4 v212, s[98:99]
	s_add_i32 m0, s49, 0xe000
	s_cmp_lg_u32 s34, 0
	global_load_lds_dwordx4 v210, s[98:99]
	s_cselect_b64 s[38:39], -1, 0
	s_cmp_eq_u32 s34, 0
	s_cbranch_scc1 .LBB0_256
	s_waitcnt vmcnt(16)
	s_cbranch_execnz .LBB0_254

.LBB0_885:
	s_waitcnt lgkmcnt(0)
	s_barrier
	s_setprio 1
	s_waitcnt lgkmcnt(0)
	v_mfma_f32_16x16x128_f8f6f4 v[126:129], v[26:33], v[58:65], v[126:129]
	v_mfma_f32_16x16x128_f8f6f4 v[122:125], v[18:25], v[58:65], v[122:125]
	v_mfma_f32_16x16x128_f8f6f4 v[110:113], v[26:33], v[50:57], v[110:113]
	v_mfma_f32_16x16x128_f8f6f4 v[106:109], v[18:25], v[50:57], v[106:109]
	v_mfma_f32_16x16x128_f8f6f4 v[94:97], v[26:33], v[42:49], v[94:97]
	v_mfma_f32_16x16x128_f8f6f4 v[90:93], v[18:25], v[42:49], v[90:93]
	v_mfma_f32_16x16x128_f8f6f4 v[78:81], v[26:33], v[34:41], v[78:81]
	v_mfma_f32_16x16x128_f8f6f4 v[74:77], v[18:25], v[34:41], v[74:77]
	s_setprio 0
	s_setprio 1
	v_mfma_f32_16x16x128_f8f6f4 v[118:121], v[10:17], v[58:65], v[118:121]
	v_mfma_f32_16x16x128_f8f6f4 v[114:117], v[2:9], v[58:65], v[114:117]
	v_mfma_f32_16x16x128_f8f6f4 v[102:105], v[10:17], v[50:57], v[102:105]
	v_mfma_f32_16x16x128_f8f6f4 v[98:101], v[2:9], v[50:57], v[98:101]
	v_mfma_f32_16x16x128_f8f6f4 v[86:89], v[10:17], v[42:49], v[86:89]
	v_mfma_f32_16x16x128_f8f6f4 v[82:85], v[2:9], v[42:49], v[82:85]
	v_mfma_f32_16x16x128_f8f6f4 v[70:73], v[10:17], v[34:41], v[70:73]
	v_mfma_f32_16x16x128_f8f6f4 v[66:69], v[2:9], v[34:41], v[66:69]
	s_setprio 0
	s_barrier
	v_add_u32_e32 v14, s48, v222
	v_add_u32_e32 v30, s53, v222
	ds_read_b128 v[2:5], v14
	ds_read_b128 v[6:9], v14 offset:1024
	ds_read_b128 v[10:13], v14 offset:2048
	ds_read_b128 v[14:17], v14 offset:3072
	ds_read_b128 v[18:21], v30
	ds_read_b128 v[22:25], v30 offset:1024
	ds_read_b128 v[26:29], v30 offset:2048
	ds_read_b128 v[30:33], v30 offset:3072
	s_add_u32 s100, s28, 0x530000
	s_addc_u32 s101, s29, 0
	s_mov_b32 m0, s42
	ds_read_b128 v[34:37], v226 offset:32768
	ds_read_b128 v[38:41], v226 offset:33792
	ds_read_b128 v[42:45], v226 offset:34816
	ds_read_b128 v[46:49], v226 offset:35840
	ds_read_b128 v[50:53], v226 offset:36864
	ds_read_b128 v[54:57], v226 offset:37888
	ds_read_b128 v[58:61], v226 offset:38912
	ds_read_b128 v[62:65], v226 offset:39936
	global_load_lds_dwordx4 v194, s[100:101]
	s_mov_b32 m0, s43
	s_nop 0
	global_load_lds_dwordx4 v198, s[100:101]
	s_waitcnt lgkmcnt(0)
	s_barrier
	s_setprio 1
	s_waitcnt lgkmcnt(0)
	v_mfma_f32_16x16x128_f8f6f4 v[190:193], v[2:9], v[34:41], v[190:193]
	v_mfma_f32_16x16x128_f8f6f4 v[186:189], v[10:17], v[34:41], v[186:189]
	v_mfma_f32_16x16x128_f8f6f4 v[174:177], v[2:9], v[42:49], v[174:177]
	v_mfma_f32_16x16x128_f8f6f4 v[170:173], v[10:17], v[42:49], v[170:173]
	v_mfma_f32_16x16x128_f8f6f4 v[158:161], v[2:9], v[50:57], v[158:161]
	v_mfma_f32_16x16x128_f8f6f4 v[154:157], v[10:17], v[50:57], v[154:157]
	v_mfma_f32_16x16x128_f8f6f4 v[142:145], v[2:9], v[58:65], v[142:145]
	v_mfma_f32_16x16x128_f8f6f4 v[138:141], v[10:17], v[58:65], v[138:141]
	s_setprio 0
	s_setprio 1
	v_mfma_f32_16x16x128_f8f6f4 v[182:185], v[18:25], v[34:41], v[182:185]
	v_mfma_f32_16x16x128_f8f6f4 v[178:181], v[26:33], v[34:41], v[178:181]
	v_mfma_f32_16x16x128_f8f6f4 v[166:169], v[18:25], v[42:49], v[166:169]
	v_mfma_f32_16x16x128_f8f6f4 v[162:165], v[26:33], v[42:49], v[162:165]
	v_mfma_f32_16x16x128_f8f6f4 v[150:153], v[18:25], v[50:57], v[150:153]
	v_mfma_f32_16x16x128_f8f6f4 v[146:149], v[26:33], v[50:57], v[146:149]
	v_mfma_f32_16x16x128_f8f6f4 v[134:137], v[18:25], v[58:65], v[134:137]
	v_mfma_f32_16x16x128_f8f6f4 v[130:133], v[26:33], v[58:65], v[130:133]
	s_setprio 0
	s_waitcnt vmcnt(8)
	s_barrier
	s_mov_b32 m0, s49
	ds_read_b128 v[34:37], v226 offset:49152
	ds_read_b128 v[38:41], v226 offset:50176
	ds_read_b128 v[42:45], v226 offset:51200
	ds_read_b128 v[46:49], v226 offset:52224
	ds_read_b128 v[50:53], v226 offset:53248
	ds_read_b128 v[54:57], v226 offset:54272
	ds_read_b128 v[58:61], v226 offset:55296
	ds_read_b128 v[62:65], v226 offset:56320
	s_add_u32 s98, s26, 0x80
	s_addc_u32 s99, s27, 0
	global_load_lds_dwordx4 v196, s[98:99]
	s_mov_b32 m0, s50
	s_nop 0
	global_load_lds_dwordx4 v200, s[98:99]
	s_mov_b32 m0, s54
	s_add_u32 s100, s72, 0x80
	s_addc_u32 s101, s73, 0
	global_load_lds_dwordx4 v196, s[100:101]
	s_mov_b32 m0, s55
	s_nop 0
	global_load_lds_dwordx4 v200, s[100:101]
	s_mov_b32 m0, s51
	s_add_u32 s98, s28, 0x100
	s_addc_u32 s99, s29, 0
	global_load_lds_dwordx4 v194, s[98:99]
	s_mov_b32 m0, s52
	s_nop 0
	global_load_lds_dwordx4 v198, s[98:99]
	s_waitcnt lgkmcnt(0)
	s_barrier
	s_setprio 1
	s_waitcnt lgkmcnt(0)
	v_mfma_f32_16x16x128_f8f6f4 v[126:129], v[2:9], v[34:41], v[126:129]
	v_mfma_f32_16x16x128_f8f6f4 v[122:125], v[10:17], v[34:41], v[122:125]
	v_mfma_f32_16x16x128_f8f6f4 v[110:113], v[2:9], v[42:49], v[110:113]
	v_mfma_f32_16x16x128_f8f6f4 v[106:109], v[10:17], v[42:49], v[106:109]
	v_mfma_f32_16x16x128_f8f6f4 v[94:97], v[2:9], v[50:57], v[94:97]
	v_mfma_f32_16x16x128_f8f6f4 v[90:93], v[10:17], v[50:57], v[90:93]
	v_mfma_f32_16x16x128_f8f6f4 v[78:81], v[2:9], v[58:65], v[78:81]
	v_mfma_f32_16x16x128_f8f6f4 v[74:77], v[10:17], v[58:65], v[74:77]
	s_setprio 0
	s_setprio 1
	v_mfma_f32_16x16x128_f8f6f4 v[118:121], v[18:25], v[34:41], v[118:121]
	v_mfma_f32_16x16x128_f8f6f4 v[114:117], v[26:33], v[34:41], v[114:117]
	v_mfma_f32_16x16x128_f8f6f4 v[102:105], v[18:25], v[42:49], v[102:105]
	v_mfma_f32_16x16x128_f8f6f4 v[98:101], v[26:33], v[42:49], v[98:101]
	v_mfma_f32_16x16x128_f8f6f4 v[86:89], v[18:25], v[50:57], v[86:89]
	v_mfma_f32_16x16x128_f8f6f4 v[82:85], v[26:33], v[50:57], v[82:85]
	v_mfma_f32_16x16x128_f8f6f4 v[70:73], v[18:25], v[58:65], v[70:73]
	v_mfma_f32_16x16x128_f8f6f4 v[66:69], v[26:33], v[58:65], v[66:69]
	s_setprio 0
	s_waitcnt vmcnt(8)
	s_barrier
	s_add_i32 s70, s70, 2
	s_add_u32 s6, s6, 0x200
	s_addc_u32 s7, s7, 0
	s_add_u32 s68, s68, 0x100
	s_addc_u32 s69, s69, 0
	s_cmp_gt_u32 s70, 13
	s_cbranch_scc1 .LBB0_893
.LBB0_886:
	s_cmp_eq_u32 s6, 0
	s_cselect_b64 s[26:27], -1, 0
	s_and_b64 s[26:27], s[0:1], s[26:27]
	s_and_b32 s26, s26, 1
	ds_read_b128 v[26:29], v224
	ds_read_b128 v[30:33], v224 offset:1024
	ds_read_b128 v[18:21], v224 offset:2048
	ds_read_b128 v[22:25], v224 offset:3072
	ds_read_b128 v[10:13], v225
	ds_read_b128 v[14:17], v225 offset:1024
	ds_read_b128 v[2:5], v225 offset:2048
	ds_read_b128 v[6:9], v225 offset:3072
	s_add_u32 s98, s4, s6
	s_addc_u32 s99, s5, s7
	s_add_i32 m0, s40, 0xc000
	ds_read_b128 v[58:61], v226
	ds_read_b128 v[62:65], v226 offset:1024
	ds_read_b128 v[50:53], v226 offset:2048
	ds_read_b128 v[54:57], v226 offset:3072
	ds_read_b128 v[42:45], v226 offset:4096
	ds_read_b128 v[46:49], v226 offset:5120
	ds_read_b128 v[34:37], v226 offset:6144
	ds_read_b128 v[38:41], v226 offset:7168
	global_load_lds_dwordx4 v204, s[98:99]
	s_add_i32 m0, s40, 0xe000
	s_cmp_lg_u32 s26, 0
	global_load_lds_dwordx4 v202, s[98:99]
	s_cselect_b64 s[30:31], -1, 0
	s_cmp_eq_u32 s26, 0
	s_cbranch_scc1 .LBB0_891
	s_waitcnt vmcnt(24)
	s_cbranch_execnz .LBB0_889

.LBB0_1062:
	s_waitcnt lgkmcnt(0)
	s_barrier
	s_setprio 1
	s_waitcnt lgkmcnt(0)
	v_mfma_f32_16x16x128_f8f6f4 v[126:129], v[26:33], v[58:65], v[126:129]
	v_mfma_f32_16x16x128_f8f6f4 v[122:125], v[18:25], v[58:65], v[122:125]
	v_mfma_f32_16x16x128_f8f6f4 v[114:117], v[26:33], v[50:57], v[114:117]
	v_mfma_f32_16x16x128_f8f6f4 v[106:109], v[18:25], v[50:57], v[106:109]
	v_mfma_f32_16x16x128_f8f6f4 v[98:101], v[26:33], v[42:49], v[98:101]
	v_mfma_f32_16x16x128_f8f6f4 v[90:93], v[18:25], v[42:49], v[90:93]
	v_mfma_f32_16x16x128_f8f6f4 v[82:85], v[26:33], v[34:41], v[82:85]
	v_mfma_f32_16x16x128_f8f6f4 v[74:77], v[18:25], v[34:41], v[74:77]
	s_setprio 0
	s_setprio 1
	v_mfma_f32_16x16x128_f8f6f4 v[118:121], v[10:17], v[58:65], v[118:121]
	v_mfma_f32_16x16x128_f8f6f4 v[110:113], v[2:9], v[58:65], v[110:113]
	v_mfma_f32_16x16x128_f8f6f4 v[102:105], v[10:17], v[50:57], v[102:105]
	v_mfma_f32_16x16x128_f8f6f4 v[94:97], v[2:9], v[50:57], v[94:97]
	v_mfma_f32_16x16x128_f8f6f4 v[86:89], v[10:17], v[42:49], v[86:89]
	v_mfma_f32_16x16x128_f8f6f4 v[78:81], v[2:9], v[42:49], v[78:81]
	v_mfma_f32_16x16x128_f8f6f4 v[70:73], v[10:17], v[34:41], v[70:73]
	v_mfma_f32_16x16x128_f8f6f4 v[66:69], v[2:9], v[34:41], v[66:69]
	s_setprio 0
	s_barrier
	v_add_u32_e32 v14, s58, v222
	v_add_u32_e32 v30, s63, v222
	ds_read_b128 v[2:5], v14
	ds_read_b128 v[6:9], v14 offset:1024
	ds_read_b128 v[10:13], v14 offset:2048
	ds_read_b128 v[14:17], v14 offset:3072
	ds_read_b128 v[18:21], v30
	ds_read_b128 v[22:25], v30 offset:1024
	ds_read_b128 v[26:29], v30 offset:2048
	ds_read_b128 v[30:33], v30 offset:3072
	s_add_u32 s100, s40, 0x40000
	s_addc_u32 s101, s41, 0
	s_mov_b32 m0, s56
	ds_read_b128 v[34:37], v226 offset:32768
	ds_read_b128 v[38:41], v226 offset:33792
	ds_read_b128 v[42:45], v226 offset:34816
	ds_read_b128 v[46:49], v226 offset:35840
	ds_read_b128 v[50:53], v226 offset:36864
	ds_read_b128 v[54:57], v226 offset:37888
	ds_read_b128 v[58:61], v226 offset:38912
	ds_read_b128 v[62:65], v226 offset:39936
	global_load_lds_dwordx4 v200, s[100:101]
	s_mov_b32 m0, s57
	s_nop 0
	global_load_lds_dwordx4 v196, s[100:101]
	s_waitcnt lgkmcnt(0)
	s_barrier
	s_setprio 1
	s_waitcnt lgkmcnt(0)
	v_mfma_f32_16x16x128_f8f6f4 v[190:193], v[2:9], v[34:41], v[190:193]
	v_mfma_f32_16x16x128_f8f6f4 v[186:189], v[10:17], v[34:41], v[186:189]
	v_mfma_f32_16x16x128_f8f6f4 v[178:181], v[2:9], v[42:49], v[178:181]
	v_mfma_f32_16x16x128_f8f6f4 v[170:173], v[10:17], v[42:49], v[170:173]
	v_mfma_f32_16x16x128_f8f6f4 v[162:165], v[2:9], v[50:57], v[162:165]
	v_mfma_f32_16x16x128_f8f6f4 v[154:157], v[10:17], v[50:57], v[154:157]
	v_mfma_f32_16x16x128_f8f6f4 v[146:149], v[2:9], v[58:65], v[146:149]
	v_mfma_f32_16x16x128_f8f6f4 v[138:141], v[10:17], v[58:65], v[138:141]
	s_setprio 0
	s_setprio 1
	v_mfma_f32_16x16x128_f8f6f4 v[182:185], v[18:25], v[34:41], v[182:185]
	v_mfma_f32_16x16x128_f8f6f4 v[174:177], v[26:33], v[34:41], v[174:177]
	v_mfma_f32_16x16x128_f8f6f4 v[166:169], v[18:25], v[42:49], v[166:169]
	v_mfma_f32_16x16x128_f8f6f4 v[158:161], v[26:33], v[42:49], v[158:161]
	v_mfma_f32_16x16x128_f8f6f4 v[150:153], v[18:25], v[50:57], v[150:153]
	v_mfma_f32_16x16x128_f8f6f4 v[142:145], v[26:33], v[50:57], v[142:145]
	v_mfma_f32_16x16x128_f8f6f4 v[134:137], v[18:25], v[58:65], v[134:137]
	v_mfma_f32_16x16x128_f8f6f4 v[130:133], v[26:33], v[58:65], v[130:133]
	s_setprio 0
	s_waitcnt vmcnt(8)
	s_barrier
	s_mov_b32 m0, s59
	ds_read_b128 v[34:37], v226 offset:49152
	ds_read_b128 v[38:41], v226 offset:50176
	ds_read_b128 v[42:45], v226 offset:51200
	ds_read_b128 v[46:49], v226 offset:52224
	ds_read_b128 v[50:53], v226 offset:53248
	ds_read_b128 v[54:57], v226 offset:54272
	ds_read_b128 v[58:61], v226 offset:55296
	ds_read_b128 v[62:65], v226 offset:56320
	s_add_u32 s98, s38, 0x80
	s_addc_u32 s99, s39, 0
	global_load_lds_dwordx4 v198, s[98:99]
	s_mov_b32 m0, s60
	s_nop 0
	global_load_lds_dwordx4 v194, s[98:99]
	s_mov_b32 m0, s64
	s_add_u32 s100, s78, 0x80
	s_addc_u32 s101, s79, 0
	global_load_lds_dwordx4 v198, s[100:101]
	s_mov_b32 m0, s65
	s_nop 0
	global_load_lds_dwordx4 v194, s[100:101]
	s_mov_b32 m0, s61
	s_add_u32 s98, s40, 0x80
	s_addc_u32 s99, s41, 0
	global_load_lds_dwordx4 v200, s[98:99]
	s_mov_b32 m0, s62
	s_nop 0
	global_load_lds_dwordx4 v196, s[98:99]
	s_waitcnt lgkmcnt(0)
	s_barrier
	s_setprio 1
	s_waitcnt lgkmcnt(0)
	v_mfma_f32_16x16x128_f8f6f4 v[126:129], v[2:9], v[34:41], v[126:129]
	v_mfma_f32_16x16x128_f8f6f4 v[122:125], v[10:17], v[34:41], v[122:125]
	v_mfma_f32_16x16x128_f8f6f4 v[114:117], v[2:9], v[42:49], v[114:117]
	v_mfma_f32_16x16x128_f8f6f4 v[106:109], v[10:17], v[42:49], v[106:109]
	v_mfma_f32_16x16x128_f8f6f4 v[98:101], v[2:9], v[50:57], v[98:101]
	v_mfma_f32_16x16x128_f8f6f4 v[90:93], v[10:17], v[50:57], v[90:93]
	v_mfma_f32_16x16x128_f8f6f4 v[82:85], v[2:9], v[58:65], v[82:85]
	v_mfma_f32_16x16x128_f8f6f4 v[74:77], v[10:17], v[58:65], v[74:77]
	s_setprio 0
	s_setprio 1
	v_mfma_f32_16x16x128_f8f6f4 v[118:121], v[18:25], v[34:41], v[118:121]
	v_mfma_f32_16x16x128_f8f6f4 v[110:113], v[26:33], v[34:41], v[110:113]
	v_mfma_f32_16x16x128_f8f6f4 v[102:105], v[18:25], v[42:49], v[102:105]
	v_mfma_f32_16x16x128_f8f6f4 v[94:97], v[26:33], v[42:49], v[94:97]
	v_mfma_f32_16x16x128_f8f6f4 v[86:89], v[18:25], v[50:57], v[86:89]
	v_mfma_f32_16x16x128_f8f6f4 v[78:81], v[26:33], v[50:57], v[78:81]
	v_mfma_f32_16x16x128_f8f6f4 v[70:73], v[18:25], v[58:65], v[70:73]
	v_mfma_f32_16x16x128_f8f6f4 v[66:69], v[26:33], v[58:65], v[66:69]
	s_setprio 0
	s_waitcnt vmcnt(8)
	s_barrier
	s_add_i32 s77, s77, 2
	s_add_u32 s36, s36, 0x100
	s_addc_u32 s37, s37, 0
	s_cmp_gt_u32 s77, 13
	s_cbranch_scc1 .LBB0_1070
.LBB0_1063:
	s_cmp_eq_u32 s36, 0
	s_cselect_b64 s[38:39], -1, 0
	s_and_b64 s[38:39], s[34:35], s[38:39]
	s_and_b32 s38, s38, 1
	ds_read_b128 v[26:29], v224
	ds_read_b128 v[30:33], v224 offset:1024
	ds_read_b128 v[18:21], v224 offset:2048
	ds_read_b128 v[22:25], v224 offset:3072
	ds_read_b128 v[10:13], v225
	ds_read_b128 v[14:17], v225 offset:1024
	ds_read_b128 v[2:5], v225 offset:2048
	ds_read_b128 v[6:9], v225 offset:3072
	s_add_u32 s98, s30, s36
	s_addc_u32 s99, s31, s37
	s_add_i32 m0, s54, 0xc000
	ds_read_b128 v[58:61], v226
	ds_read_b128 v[62:65], v226 offset:1024
	ds_read_b128 v[50:53], v226 offset:2048
	ds_read_b128 v[54:57], v226 offset:3072
	ds_read_b128 v[42:45], v226 offset:4096
	ds_read_b128 v[46:49], v226 offset:5120
	ds_read_b128 v[34:37], v226 offset:6144
	ds_read_b128 v[38:41], v226 offset:7168
	global_load_lds_dwordx4 v204, s[98:99]
	s_add_i32 m0, s54, 0xe000
	s_cmp_lg_u32 s38, 0
	global_load_lds_dwordx4 v202, s[98:99]
	s_cselect_b64 s[42:43], -1, 0
	s_cmp_eq_u32 s38, 0
	s_cbranch_scc1 .LBB0_1068
	s_waitcnt vmcnt(24)
	s_cbranch_execnz .LBB0_1066

.LBB0_1225:
	s_waitcnt lgkmcnt(0)
	s_barrier
	s_setprio 1
	s_waitcnt lgkmcnt(0)
	v_mfma_f32_16x16x32_bf16 v[54:57], v[82:85], v[186:189], v[54:57]
	v_mfma_f32_16x16x32_bf16 v[46:49], v[90:93], v[186:189], v[46:49]
	v_mfma_f32_16x16x32_bf16 v[50:53], v[82:85], v[178:181], v[50:53]
	v_mfma_f32_16x16x32_bf16 v[38:41], v[90:93], v[178:181], v[38:41]
	v_mfma_f32_16x16x32_bf16 v[30:33], v[82:85], v[170:173], v[30:33]
	v_mfma_f32_16x16x32_bf16 v[22:25], v[90:93], v[170:173], v[22:25]
	v_mfma_f32_16x16x32_bf16 v[14:17], v[82:85], v[162:165], v[14:17]
	v_mfma_f32_16x16x32_bf16 v[10:13], v[90:93], v[162:165], v[10:13]
	v_mfma_f32_16x16x32_bf16 v[54:57], v[86:89], v[190:193], v[54:57]
	v_mfma_f32_16x16x32_bf16 v[46:49], v[94:97], v[190:193], v[46:49]
	v_mfma_f32_16x16x32_bf16 v[50:53], v[86:89], v[182:185], v[50:53]
	v_mfma_f32_16x16x32_bf16 v[38:41], v[94:97], v[182:185], v[38:41]
	v_mfma_f32_16x16x32_bf16 v[30:33], v[86:89], v[174:177], v[30:33]
	v_mfma_f32_16x16x32_bf16 v[22:25], v[94:97], v[174:177], v[22:25]
	v_mfma_f32_16x16x32_bf16 v[14:17], v[86:89], v[166:169], v[14:17]
	v_mfma_f32_16x16x32_bf16 v[10:13], v[94:97], v[166:169], v[10:13]
	s_setprio 0
	s_setprio 1
	v_mfma_f32_16x16x32_bf16 v[62:65], v[66:69], v[186:189], v[62:65]
	v_mfma_f32_16x16x32_bf16 v[58:61], v[74:77], v[186:189], v[58:61]
	v_mfma_f32_16x16x32_bf16 v[42:45], v[66:69], v[178:181], v[42:45]
	v_mfma_f32_16x16x32_bf16 v[34:37], v[74:77], v[178:181], v[34:37]
	v_mfma_f32_16x16x32_bf16 v[26:29], v[66:69], v[170:173], v[26:29]
	v_mfma_f32_16x16x32_bf16 v[18:21], v[74:77], v[170:173], v[18:21]
	v_mfma_f32_16x16x32_bf16 v[6:9], v[66:69], v[162:165], v[6:9]
	v_mfma_f32_16x16x32_bf16 v[2:5], v[74:77], v[162:165], v[2:5]
	v_mfma_f32_16x16x32_bf16 v[62:65], v[70:73], v[190:193], v[62:65]
	v_mfma_f32_16x16x32_bf16 v[58:61], v[78:81], v[190:193], v[58:61]
	v_mfma_f32_16x16x32_bf16 v[42:45], v[70:73], v[182:185], v[42:45]
	v_mfma_f32_16x16x32_bf16 v[34:37], v[78:81], v[182:185], v[34:37]
	v_mfma_f32_16x16x32_bf16 v[26:29], v[70:73], v[174:177], v[26:29]
	v_mfma_f32_16x16x32_bf16 v[18:21], v[78:81], v[174:177], v[18:21]
	v_mfma_f32_16x16x32_bf16 v[6:9], v[70:73], v[166:169], v[6:9]
	v_mfma_f32_16x16x32_bf16 v[2:5], v[78:81], v[166:169], v[2:5]
	s_setprio 0
	s_barrier
	v_add_u32_e32 v78, s74, v1
	v_add_u32_e32 v94, s79, v1
	ds_read_b128 v[66:69], v78
	ds_read_b128 v[70:73], v78 offset:1024
	ds_read_b128 v[74:77], v78 offset:2048
	ds_read_b128 v[78:81], v78 offset:3072
	ds_read_b128 v[82:85], v94
	ds_read_b128 v[86:89], v94 offset:1024
	ds_read_b128 v[90:93], v94 offset:2048
	ds_read_b128 v[94:97], v94 offset:3072
	s_add_u32 s100, s54, 0x80000
	s_addc_u32 s101, s55, 0
	s_mov_b32 m0, s70
	ds_read_b128 v[162:165], v231 offset:32768
	ds_read_b128 v[166:169], v231 offset:33792
	ds_read_b128 v[170:173], v231 offset:34816
	ds_read_b128 v[174:177], v231 offset:35840
	ds_read_b128 v[178:181], v231 offset:36864
	ds_read_b128 v[182:185], v231 offset:37888
	ds_read_b128 v[186:189], v231 offset:38912
	ds_read_b128 v[190:193], v231 offset:39936
	global_load_lds_dwordx4 v194, s[100:101]
	s_mov_b32 m0, s71
	s_nop 0
	global_load_lds_dwordx4 v198, s[100:101]
	s_waitcnt lgkmcnt(0)
	s_barrier
	s_setprio 1
	s_waitcnt lgkmcnt(0)
	v_mfma_f32_16x16x32_bf16 v[150:153], v[66:69], v[162:165], v[150:153]
	v_mfma_f32_16x16x32_bf16 v[142:145], v[74:77], v[162:165], v[142:145]
	v_mfma_f32_16x16x32_bf16 v[146:149], v[66:69], v[170:173], v[146:149]
	v_mfma_f32_16x16x32_bf16 v[134:137], v[74:77], v[170:173], v[134:137]
	v_mfma_f32_16x16x32_bf16 v[126:129], v[66:69], v[178:181], v[126:129]
	v_mfma_f32_16x16x32_bf16 v[118:121], v[74:77], v[178:181], v[118:121]
	v_mfma_f32_16x16x32_bf16 v[110:113], v[66:69], v[186:189], v[110:113]
	v_mfma_f32_16x16x32_bf16 v[106:109], v[74:77], v[186:189], v[106:109]
	v_mfma_f32_16x16x32_bf16 v[150:153], v[70:73], v[166:169], v[150:153]
	v_mfma_f32_16x16x32_bf16 v[142:145], v[78:81], v[166:169], v[142:145]
	v_mfma_f32_16x16x32_bf16 v[146:149], v[70:73], v[174:177], v[146:149]
	v_mfma_f32_16x16x32_bf16 v[134:137], v[78:81], v[174:177], v[134:137]
	v_mfma_f32_16x16x32_bf16 v[126:129], v[70:73], v[182:185], v[126:129]
	v_mfma_f32_16x16x32_bf16 v[118:121], v[78:81], v[182:185], v[118:121]
	v_mfma_f32_16x16x32_bf16 v[110:113], v[70:73], v[190:193], v[110:113]
	v_mfma_f32_16x16x32_bf16 v[106:109], v[78:81], v[190:193], v[106:109]
	s_setprio 0
	s_setprio 1
	v_mfma_f32_16x16x32_bf16 v[158:161], v[82:85], v[162:165], v[158:161]
	v_mfma_f32_16x16x32_bf16 v[154:157], v[90:93], v[162:165], v[154:157]
	v_mfma_f32_16x16x32_bf16 v[138:141], v[82:85], v[170:173], v[138:141]
	v_mfma_f32_16x16x32_bf16 v[130:133], v[90:93], v[170:173], v[130:133]
	v_mfma_f32_16x16x32_bf16 v[122:125], v[82:85], v[178:181], v[122:125]
	v_mfma_f32_16x16x32_bf16 v[114:117], v[90:93], v[178:181], v[114:117]
	v_mfma_f32_16x16x32_bf16 v[102:105], v[82:85], v[186:189], v[102:105]
	v_mfma_f32_16x16x32_bf16 v[98:101], v[90:93], v[186:189], v[98:101]
	v_mfma_f32_16x16x32_bf16 v[158:161], v[86:89], v[166:169], v[158:161]
	v_mfma_f32_16x16x32_bf16 v[154:157], v[94:97], v[166:169], v[154:157]
	v_mfma_f32_16x16x32_bf16 v[138:141], v[86:89], v[174:177], v[138:141]
	v_mfma_f32_16x16x32_bf16 v[130:133], v[94:97], v[174:177], v[130:133]
	v_mfma_f32_16x16x32_bf16 v[122:125], v[86:89], v[182:185], v[122:125]
	v_mfma_f32_16x16x32_bf16 v[114:117], v[94:97], v[182:185], v[114:117]
	v_mfma_f32_16x16x32_bf16 v[102:105], v[86:89], v[190:193], v[102:105]
	v_mfma_f32_16x16x32_bf16 v[98:101], v[94:97], v[190:193], v[98:101]
	s_setprio 0
	s_waitcnt vmcnt(8)
	s_barrier
	s_mov_b32 m0, s75
	ds_read_b128 v[162:165], v231 offset:49152
	ds_read_b128 v[166:169], v231 offset:50176
	ds_read_b128 v[170:173], v231 offset:51200
	ds_read_b128 v[174:177], v231 offset:52224
	ds_read_b128 v[178:181], v231 offset:53248
	ds_read_b128 v[182:185], v231 offset:54272
	ds_read_b128 v[186:189], v231 offset:55296
	ds_read_b128 v[190:193], v231 offset:56320
	s_add_u32 s98, s52, 0x80
	s_addc_u32 s99, s53, 0
	global_load_lds_dwordx4 v196, s[98:99]
	s_mov_b32 m0, s76
	s_nop 0
	global_load_lds_dwordx4 v200, s[98:99]
	s_mov_b32 m0, s80
	s_add_u32 s100, s94, 0x80
	s_addc_u32 s101, s95, 0
	global_load_lds_dwordx4 v196, s[100:101]
	s_mov_b32 m0, s81
	s_nop 0
	global_load_lds_dwordx4 v200, s[100:101]
	s_mov_b32 m0, s77
	s_add_u32 s98, s54, 0x80
	s_addc_u32 s99, s55, 0
	global_load_lds_dwordx4 v194, s[98:99]
	s_mov_b32 m0, s78
	s_nop 0
	global_load_lds_dwordx4 v198, s[98:99]
	s_waitcnt lgkmcnt(0)
	s_barrier
	s_setprio 1
	s_waitcnt lgkmcnt(0)
	v_mfma_f32_16x16x32_bf16 v[54:57], v[66:69], v[162:165], v[54:57]
	v_mfma_f32_16x16x32_bf16 v[46:49], v[74:77], v[162:165], v[46:49]
	v_mfma_f32_16x16x32_bf16 v[50:53], v[66:69], v[170:173], v[50:53]
	v_mfma_f32_16x16x32_bf16 v[38:41], v[74:77], v[170:173], v[38:41]
	v_mfma_f32_16x16x32_bf16 v[30:33], v[66:69], v[178:181], v[30:33]
	v_mfma_f32_16x16x32_bf16 v[22:25], v[74:77], v[178:181], v[22:25]
	v_mfma_f32_16x16x32_bf16 v[14:17], v[66:69], v[186:189], v[14:17]
	v_mfma_f32_16x16x32_bf16 v[10:13], v[74:77], v[186:189], v[10:13]
	v_mfma_f32_16x16x32_bf16 v[54:57], v[70:73], v[166:169], v[54:57]
	v_mfma_f32_16x16x32_bf16 v[46:49], v[78:81], v[166:169], v[46:49]
	v_mfma_f32_16x16x32_bf16 v[50:53], v[70:73], v[174:177], v[50:53]
	v_mfma_f32_16x16x32_bf16 v[38:41], v[78:81], v[174:177], v[38:41]
	v_mfma_f32_16x16x32_bf16 v[30:33], v[70:73], v[182:185], v[30:33]
	v_mfma_f32_16x16x32_bf16 v[22:25], v[78:81], v[182:185], v[22:25]
	v_mfma_f32_16x16x32_bf16 v[14:17], v[70:73], v[190:193], v[14:17]
	v_mfma_f32_16x16x32_bf16 v[10:13], v[78:81], v[190:193], v[10:13]
	s_setprio 0
	s_setprio 1
	v_mfma_f32_16x16x32_bf16 v[62:65], v[82:85], v[162:165], v[62:65]
	v_mfma_f32_16x16x32_bf16 v[58:61], v[90:93], v[162:165], v[58:61]
	v_mfma_f32_16x16x32_bf16 v[42:45], v[82:85], v[170:173], v[42:45]
	v_mfma_f32_16x16x32_bf16 v[34:37], v[90:93], v[170:173], v[34:37]
	v_mfma_f32_16x16x32_bf16 v[26:29], v[82:85], v[178:181], v[26:29]
	v_mfma_f32_16x16x32_bf16 v[18:21], v[90:93], v[178:181], v[18:21]
	v_mfma_f32_16x16x32_bf16 v[6:9], v[82:85], v[186:189], v[6:9]
	v_mfma_f32_16x16x32_bf16 v[2:5], v[90:93], v[186:189], v[2:5]
	v_mfma_f32_16x16x32_bf16 v[62:65], v[86:89], v[166:169], v[62:65]
	v_mfma_f32_16x16x32_bf16 v[58:61], v[94:97], v[166:169], v[58:61]
	v_mfma_f32_16x16x32_bf16 v[42:45], v[86:89], v[174:177], v[42:45]
	v_mfma_f32_16x16x32_bf16 v[34:37], v[94:97], v[174:177], v[34:37]
	v_mfma_f32_16x16x32_bf16 v[26:29], v[86:89], v[182:185], v[26:29]
	v_mfma_f32_16x16x32_bf16 v[18:21], v[94:97], v[182:185], v[18:21]
	v_mfma_f32_16x16x32_bf16 v[6:9], v[86:89], v[190:193], v[6:9]
	v_mfma_f32_16x16x32_bf16 v[2:5], v[94:97], v[190:193], v[2:5]
	s_setprio 0
	s_waitcnt vmcnt(8)
	s_barrier
	s_add_i32 s93, s93, 2
	s_add_u32 s50, s50, 0x100
	s_addc_u32 s51, s51, 0
	s_cmp_gt_u32 s93, 29
	s_cbranch_scc1 .LBB0_1233
.LBB0_1226:
	s_cmp_eq_u32 s50, 0
	s_cselect_b64 s[52:53], -1, 0
	s_and_b64 s[52:53], s[48:49], s[52:53]
	s_and_b32 s52, s52, 1
	ds_read_b128 v[82:85], v228
	ds_read_b128 v[86:89], v228 offset:1024
	ds_read_b128 v[90:93], v228 offset:2048
	ds_read_b128 v[94:97], v228 offset:3072
	ds_read_b128 v[66:69], v229
	ds_read_b128 v[70:73], v229 offset:1024
	ds_read_b128 v[74:77], v229 offset:2048
	ds_read_b128 v[78:81], v229 offset:3072
	s_add_u32 s98, s46, s50
	s_addc_u32 s99, s47, s51
	s_add_i32 m0, s68, 0xc000
	ds_read_b128 v[186:189], v231
	ds_read_b128 v[190:193], v231 offset:1024
	ds_read_b128 v[178:181], v231 offset:2048
	ds_read_b128 v[182:185], v231 offset:3072
	ds_read_b128 v[170:173], v231 offset:4096
	ds_read_b128 v[174:177], v231 offset:5120
	ds_read_b128 v[162:165], v231 offset:6144
	ds_read_b128 v[166:169], v231 offset:7168
	global_load_lds_dwordx4 v210, s[98:99]
	s_add_i32 m0, s68, 0xe000
	s_cmp_lg_u32 s52, 0
	global_load_lds_dwordx4 v208, s[98:99]
	s_cselect_b64 s[56:57], -1, 0
	s_cmp_eq_u32 s52, 0
	s_cbranch_scc1 .LBB0_1231
	s_waitcnt vmcnt(24)
	s_cbranch_execnz .LBB0_1229

.LBB0_1397:
	s_waitcnt lgkmcnt(0)
	s_barrier
	s_setprio 1
	s_waitcnt lgkmcnt(0)
	v_mfma_f32_16x16x32_bf16 v[62:65], v[146:149], v[186:189], v[62:65]
	v_mfma_f32_16x16x32_bf16 v[58:61], v[154:157], v[186:189], v[58:61]
	v_mfma_f32_16x16x32_bf16 v[54:57], v[146:149], v[178:181], v[54:57]
	v_mfma_f32_16x16x32_bf16 v[46:49], v[154:157], v[178:181], v[46:49]
	v_mfma_f32_16x16x32_bf16 v[38:41], v[146:149], v[170:173], v[38:41]
	v_mfma_f32_16x16x32_bf16 v[30:33], v[154:157], v[170:173], v[30:33]
	v_mfma_f32_16x16x32_bf16 v[22:25], v[146:149], v[162:165], v[22:25]
	v_mfma_f32_16x16x32_bf16 v[14:17], v[154:157], v[162:165], v[14:17]
	v_mfma_f32_16x16x32_bf16 v[62:65], v[150:153], v[190:193], v[62:65]
	v_mfma_f32_16x16x32_bf16 v[58:61], v[158:161], v[190:193], v[58:61]
	v_mfma_f32_16x16x32_bf16 v[54:57], v[150:153], v[182:185], v[54:57]
	v_mfma_f32_16x16x32_bf16 v[46:49], v[158:161], v[182:185], v[46:49]
	v_mfma_f32_16x16x32_bf16 v[38:41], v[150:153], v[174:177], v[38:41]
	v_mfma_f32_16x16x32_bf16 v[30:33], v[158:161], v[174:177], v[30:33]
	v_mfma_f32_16x16x32_bf16 v[22:25], v[150:153], v[166:169], v[22:25]
	v_mfma_f32_16x16x32_bf16 v[14:17], v[158:161], v[166:169], v[14:17]
	s_setprio 0
	s_setprio 1
	v_mfma_f32_16x16x32_bf16 v[50:53], v[130:133], v[186:189], v[50:53]
	v_mfma_f32_16x16x32_bf16 v[42:45], v[138:141], v[186:189], v[42:45]
	v_mfma_f32_16x16x32_bf16 v[34:37], v[130:133], v[178:181], v[34:37]
	v_mfma_f32_16x16x32_bf16 v[26:29], v[138:141], v[178:181], v[26:29]
	v_mfma_f32_16x16x32_bf16 v[18:21], v[130:133], v[170:173], v[18:21]
	v_mfma_f32_16x16x32_bf16 v[10:13], v[138:141], v[170:173], v[10:13]
	v_mfma_f32_16x16x32_bf16 v[6:9], v[130:133], v[162:165], v[6:9]
	v_mfma_f32_16x16x32_bf16 v[2:5], v[138:141], v[162:165], v[2:5]
	v_mfma_f32_16x16x32_bf16 v[50:53], v[134:137], v[190:193], v[50:53]
	v_mfma_f32_16x16x32_bf16 v[42:45], v[142:145], v[190:193], v[42:45]
	v_mfma_f32_16x16x32_bf16 v[34:37], v[134:137], v[182:185], v[34:37]
	v_mfma_f32_16x16x32_bf16 v[26:29], v[142:145], v[182:185], v[26:29]
	v_mfma_f32_16x16x32_bf16 v[18:21], v[134:137], v[174:177], v[18:21]
	v_mfma_f32_16x16x32_bf16 v[10:13], v[142:145], v[174:177], v[10:13]
	v_mfma_f32_16x16x32_bf16 v[6:9], v[134:137], v[166:169], v[6:9]
	v_mfma_f32_16x16x32_bf16 v[2:5], v[142:145], v[166:169], v[2:5]
	s_setprio 0
	s_barrier
	v_add_u32_e32 v142, s52, v222
	v_add_u32_e32 v158, s57, v222
	ds_read_b128 v[130:133], v142
	ds_read_b128 v[134:137], v142 offset:1024
	ds_read_b128 v[138:141], v142 offset:2048
	ds_read_b128 v[142:145], v142 offset:3072
	ds_read_b128 v[146:149], v158
	ds_read_b128 v[150:153], v158 offset:1024
	ds_read_b128 v[154:157], v158 offset:2048
	ds_read_b128 v[158:161], v158 offset:3072
	s_add_u32 s100, s30, 0x160000
	s_addc_u32 s101, s31, 0
	s_mov_b32 m0, s50
	ds_read_b128 v[162:165], v226 offset:32768
	ds_read_b128 v[166:169], v226 offset:33792
	ds_read_b128 v[170:173], v226 offset:34816
	ds_read_b128 v[174:177], v226 offset:35840
	ds_read_b128 v[178:181], v226 offset:36864
	ds_read_b128 v[182:185], v226 offset:37888
	ds_read_b128 v[186:189], v226 offset:38912
	ds_read_b128 v[190:193], v226 offset:39936
	global_load_lds_dwordx4 v200, s[100:101]
	s_mov_b32 m0, s51
	s_nop 0
	global_load_lds_dwordx4 v196, s[100:101]
	s_waitcnt lgkmcnt(0)
	s_barrier
	s_setprio 1
	s_waitcnt lgkmcnt(0)
	v_mfma_f32_16x16x32_bf16 v[126:129], v[130:133], v[162:165], v[126:129]
	v_mfma_f32_16x16x32_bf16 v[122:125], v[138:141], v[162:165], v[122:125]
	v_mfma_f32_16x16x32_bf16 v[118:121], v[130:133], v[170:173], v[118:121]
	v_mfma_f32_16x16x32_bf16 v[110:113], v[138:141], v[170:173], v[110:113]
	v_mfma_f32_16x16x32_bf16 v[102:105], v[130:133], v[178:181], v[102:105]
	v_mfma_f32_16x16x32_bf16 v[94:97], v[138:141], v[178:181], v[94:97]
	v_mfma_f32_16x16x32_bf16 v[86:89], v[130:133], v[186:189], v[86:89]
	v_mfma_f32_16x16x32_bf16 v[78:81], v[138:141], v[186:189], v[78:81]
	v_mfma_f32_16x16x32_bf16 v[126:129], v[134:137], v[166:169], v[126:129]
	v_mfma_f32_16x16x32_bf16 v[122:125], v[142:145], v[166:169], v[122:125]
	v_mfma_f32_16x16x32_bf16 v[118:121], v[134:137], v[174:177], v[118:121]
	v_mfma_f32_16x16x32_bf16 v[110:113], v[142:145], v[174:177], v[110:113]
	v_mfma_f32_16x16x32_bf16 v[102:105], v[134:137], v[182:185], v[102:105]
	v_mfma_f32_16x16x32_bf16 v[94:97], v[142:145], v[182:185], v[94:97]
	v_mfma_f32_16x16x32_bf16 v[86:89], v[134:137], v[190:193], v[86:89]
	v_mfma_f32_16x16x32_bf16 v[78:81], v[142:145], v[190:193], v[78:81]
	s_setprio 0
	s_setprio 1
	v_mfma_f32_16x16x32_bf16 v[114:117], v[146:149], v[162:165], v[114:117]
	v_mfma_f32_16x16x32_bf16 v[106:109], v[154:157], v[162:165], v[106:109]
	v_mfma_f32_16x16x32_bf16 v[98:101], v[146:149], v[170:173], v[98:101]
	v_mfma_f32_16x16x32_bf16 v[90:93], v[154:157], v[170:173], v[90:93]
	v_mfma_f32_16x16x32_bf16 v[82:85], v[146:149], v[178:181], v[82:85]
	v_mfma_f32_16x16x32_bf16 v[74:77], v[154:157], v[178:181], v[74:77]
	v_mfma_f32_16x16x32_bf16 v[70:73], v[146:149], v[186:189], v[70:73]
	v_mfma_f32_16x16x32_bf16 v[66:69], v[154:157], v[186:189], v[66:69]
	v_mfma_f32_16x16x32_bf16 v[114:117], v[150:153], v[166:169], v[114:117]
	v_mfma_f32_16x16x32_bf16 v[106:109], v[158:161], v[166:169], v[106:109]
	v_mfma_f32_16x16x32_bf16 v[98:101], v[150:153], v[174:177], v[98:101]
	v_mfma_f32_16x16x32_bf16 v[90:93], v[158:161], v[174:177], v[90:93]
	v_mfma_f32_16x16x32_bf16 v[82:85], v[150:153], v[182:185], v[82:85]
	v_mfma_f32_16x16x32_bf16 v[74:77], v[158:161], v[182:185], v[74:77]
	v_mfma_f32_16x16x32_bf16 v[70:73], v[150:153], v[190:193], v[70:73]
	v_mfma_f32_16x16x32_bf16 v[66:69], v[158:161], v[190:193], v[66:69]
	s_setprio 0
	s_waitcnt vmcnt(8)
	s_barrier
	s_mov_b32 m0, s53
	ds_read_b128 v[162:165], v226 offset:49152
	ds_read_b128 v[166:169], v226 offset:50176
	ds_read_b128 v[170:173], v226 offset:51200
	ds_read_b128 v[174:177], v226 offset:52224
	ds_read_b128 v[178:181], v226 offset:53248
	ds_read_b128 v[182:185], v226 offset:54272
	ds_read_b128 v[186:189], v226 offset:55296
	ds_read_b128 v[190:193], v226 offset:56320
	s_add_u32 s98, s28, 0x80
	s_addc_u32 s99, s29, 0
	global_load_lds_dwordx4 v198, s[98:99]
	s_mov_b32 m0, s54
	s_nop 0
	global_load_lds_dwordx4 v194, s[98:99]
	s_mov_b32 m0, s58
	s_add_u32 s100, s74, 0x80
	s_addc_u32 s101, s75, 0
	global_load_lds_dwordx4 v198, s[100:101]
	s_mov_b32 m0, s59
	s_nop 0
	global_load_lds_dwordx4 v194, s[100:101]
	s_mov_b32 m0, s55
	s_add_u32 s98, s30, 0x80
	s_addc_u32 s99, s31, 0
	global_load_lds_dwordx4 v200, s[98:99]
	s_mov_b32 m0, s56
	s_nop 0
	global_load_lds_dwordx4 v196, s[98:99]
	s_waitcnt lgkmcnt(0)
	s_barrier
	s_setprio 1
	s_waitcnt lgkmcnt(0)
	v_mfma_f32_16x16x32_bf16 v[62:65], v[130:133], v[162:165], v[62:65]
	v_mfma_f32_16x16x32_bf16 v[58:61], v[138:141], v[162:165], v[58:61]
	v_mfma_f32_16x16x32_bf16 v[54:57], v[130:133], v[170:173], v[54:57]
	v_mfma_f32_16x16x32_bf16 v[46:49], v[138:141], v[170:173], v[46:49]
	v_mfma_f32_16x16x32_bf16 v[38:41], v[130:133], v[178:181], v[38:41]
	v_mfma_f32_16x16x32_bf16 v[30:33], v[138:141], v[178:181], v[30:33]
	v_mfma_f32_16x16x32_bf16 v[22:25], v[130:133], v[186:189], v[22:25]
	v_mfma_f32_16x16x32_bf16 v[14:17], v[138:141], v[186:189], v[14:17]
	v_mfma_f32_16x16x32_bf16 v[62:65], v[134:137], v[166:169], v[62:65]
	v_mfma_f32_16x16x32_bf16 v[58:61], v[142:145], v[166:169], v[58:61]
	v_mfma_f32_16x16x32_bf16 v[54:57], v[134:137], v[174:177], v[54:57]
	v_mfma_f32_16x16x32_bf16 v[46:49], v[142:145], v[174:177], v[46:49]
	v_mfma_f32_16x16x32_bf16 v[38:41], v[134:137], v[182:185], v[38:41]
	v_mfma_f32_16x16x32_bf16 v[30:33], v[142:145], v[182:185], v[30:33]
	v_mfma_f32_16x16x32_bf16 v[22:25], v[134:137], v[190:193], v[22:25]
	v_mfma_f32_16x16x32_bf16 v[14:17], v[142:145], v[190:193], v[14:17]
	s_setprio 0
	s_setprio 1
	v_mfma_f32_16x16x32_bf16 v[50:53], v[146:149], v[162:165], v[50:53]
	v_mfma_f32_16x16x32_bf16 v[42:45], v[154:157], v[162:165], v[42:45]
	v_mfma_f32_16x16x32_bf16 v[34:37], v[146:149], v[170:173], v[34:37]
	v_mfma_f32_16x16x32_bf16 v[26:29], v[154:157], v[170:173], v[26:29]
	v_mfma_f32_16x16x32_bf16 v[18:21], v[146:149], v[178:181], v[18:21]
	v_mfma_f32_16x16x32_bf16 v[10:13], v[154:157], v[178:181], v[10:13]
	v_mfma_f32_16x16x32_bf16 v[6:9], v[146:149], v[186:189], v[6:9]
	v_mfma_f32_16x16x32_bf16 v[2:5], v[154:157], v[186:189], v[2:5]
	v_mfma_f32_16x16x32_bf16 v[50:53], v[150:153], v[166:169], v[50:53]
	v_mfma_f32_16x16x32_bf16 v[42:45], v[158:161], v[166:169], v[42:45]
	v_mfma_f32_16x16x32_bf16 v[34:37], v[150:153], v[174:177], v[34:37]
	v_mfma_f32_16x16x32_bf16 v[26:29], v[158:161], v[174:177], v[26:29]
	v_mfma_f32_16x16x32_bf16 v[18:21], v[150:153], v[182:185], v[18:21]
	v_mfma_f32_16x16x32_bf16 v[10:13], v[158:161], v[182:185], v[10:13]
	v_mfma_f32_16x16x32_bf16 v[6:9], v[150:153], v[190:193], v[6:9]
	v_mfma_f32_16x16x32_bf16 v[2:5], v[158:161], v[190:193], v[2:5]
	s_setprio 0
	s_waitcnt vmcnt(8)
	s_barrier
	s_add_i32 s72, s72, 2
	s_add_u32 s26, s26, 0x100
	s_addc_u32 s27, s27, 0
	s_cmpk_gt_u32 s72, 0x55
	s_cbranch_scc1 .LBB0_1405
.LBB0_1398:
	s_cmp_eq_u32 s26, 0
	s_cselect_b64 s[28:29], -1, 0
	s_and_b64 s[28:29], s[24:25], s[28:29]
	s_and_b32 s28, s28, 1
	ds_read_b128 v[146:149], v224
	ds_read_b128 v[150:153], v224 offset:1024
	ds_read_b128 v[154:157], v224 offset:2048
	ds_read_b128 v[158:161], v224 offset:3072
	ds_read_b128 v[130:133], v225
	ds_read_b128 v[134:137], v225 offset:1024
	ds_read_b128 v[138:141], v225 offset:2048
	ds_read_b128 v[142:145], v225 offset:3072
	s_add_u32 s98, s22, s26
	s_addc_u32 s99, s23, s27
	s_add_i32 m0, s48, 0xc000
	ds_read_b128 v[186:189], v226
	ds_read_b128 v[190:193], v226 offset:1024
	ds_read_b128 v[178:181], v226 offset:2048
	ds_read_b128 v[182:185], v226 offset:3072
	ds_read_b128 v[170:173], v226 offset:4096
	ds_read_b128 v[174:177], v226 offset:5120
	ds_read_b128 v[162:165], v226 offset:6144
	ds_read_b128 v[166:169], v226 offset:7168
	global_load_lds_dwordx4 v204, s[98:99]
	s_add_i32 m0, s48, 0xe000
	s_cmp_lg_u32 s28, 0
	global_load_lds_dwordx4 v202, s[98:99]
	s_cselect_b64 s[34:35], -1, 0
	s_cmp_eq_u32 s28, 0
	s_cbranch_scc1 .LBB0_1403
	s_waitcnt vmcnt(24)
	s_cbranch_execnz .LBB0_1401

.LBB0_2224:
	s_waitcnt lgkmcnt(0)
	s_barrier
	s_setprio 1
	s_waitcnt lgkmcnt(0)
	v_mfma_f32_16x16x128_f8f6f4 v[126:129], v[26:33], v[58:65], v[126:129]
	v_mfma_f32_16x16x128_f8f6f4 v[122:125], v[18:25], v[58:65], v[122:125]
	v_mfma_f32_16x16x128_f8f6f4 v[110:113], v[26:33], v[50:57], v[110:113]
	v_mfma_f32_16x16x128_f8f6f4 v[106:109], v[18:25], v[50:57], v[106:109]
	v_mfma_f32_16x16x128_f8f6f4 v[94:97], v[26:33], v[42:49], v[94:97]
	v_mfma_f32_16x16x128_f8f6f4 v[90:93], v[18:25], v[42:49], v[90:93]
	v_mfma_f32_16x16x128_f8f6f4 v[78:81], v[26:33], v[34:41], v[78:81]
	v_mfma_f32_16x16x128_f8f6f4 v[74:77], v[18:25], v[34:41], v[74:77]
	s_setprio 0
	s_setprio 1
	v_mfma_f32_16x16x128_f8f6f4 v[118:121], v[10:17], v[58:65], v[118:121]
	v_mfma_f32_16x16x128_f8f6f4 v[114:117], v[2:9], v[58:65], v[114:117]
	v_mfma_f32_16x16x128_f8f6f4 v[102:105], v[10:17], v[50:57], v[102:105]
	v_mfma_f32_16x16x128_f8f6f4 v[98:101], v[2:9], v[50:57], v[98:101]
	v_mfma_f32_16x16x128_f8f6f4 v[86:89], v[10:17], v[42:49], v[86:89]
	v_mfma_f32_16x16x128_f8f6f4 v[82:85], v[2:9], v[42:49], v[82:85]
	v_mfma_f32_16x16x128_f8f6f4 v[70:73], v[10:17], v[34:41], v[70:73]
	v_mfma_f32_16x16x128_f8f6f4 v[66:69], v[2:9], v[34:41], v[66:69]
	s_setprio 0
	s_barrier
	v_add_u32_e32 v14, s48, v222
	v_add_u32_e32 v30, s53, v222
	ds_read_b128 v[2:5], v14
	ds_read_b128 v[6:9], v14 offset:1024
	ds_read_b128 v[10:13], v14 offset:2048
	ds_read_b128 v[14:17], v14 offset:3072
	ds_read_b128 v[18:21], v30
	ds_read_b128 v[22:25], v30 offset:1024
	ds_read_b128 v[26:29], v30 offset:2048
	ds_read_b128 v[30:33], v30 offset:3072
	s_add_u32 s100, s28, 0x530000
	s_addc_u32 s101, s29, 0
	s_mov_b32 m0, s42
	ds_read_b128 v[34:37], v226 offset:32768
	ds_read_b128 v[38:41], v226 offset:33792
	ds_read_b128 v[42:45], v226 offset:34816
	ds_read_b128 v[46:49], v226 offset:35840
	ds_read_b128 v[50:53], v226 offset:36864
	ds_read_b128 v[54:57], v226 offset:37888
	ds_read_b128 v[58:61], v226 offset:38912
	ds_read_b128 v[62:65], v226 offset:39936
	global_load_lds_dwordx4 v194, s[100:101]
	s_mov_b32 m0, s43
	s_nop 0
	global_load_lds_dwordx4 v198, s[100:101]
	s_waitcnt lgkmcnt(0)
	s_barrier
	s_setprio 1
	s_waitcnt lgkmcnt(0)
	v_mfma_f32_16x16x128_f8f6f4 v[190:193], v[2:9], v[34:41], v[190:193]
	v_mfma_f32_16x16x128_f8f6f4 v[186:189], v[10:17], v[34:41], v[186:189]
	v_mfma_f32_16x16x128_f8f6f4 v[174:177], v[2:9], v[42:49], v[174:177]
	v_mfma_f32_16x16x128_f8f6f4 v[170:173], v[10:17], v[42:49], v[170:173]
	v_mfma_f32_16x16x128_f8f6f4 v[158:161], v[2:9], v[50:57], v[158:161]
	v_mfma_f32_16x16x128_f8f6f4 v[154:157], v[10:17], v[50:57], v[154:157]
	v_mfma_f32_16x16x128_f8f6f4 v[142:145], v[2:9], v[58:65], v[142:145]
	v_mfma_f32_16x16x128_f8f6f4 v[138:141], v[10:17], v[58:65], v[138:141]
	s_setprio 0
	s_setprio 1
	v_mfma_f32_16x16x128_f8f6f4 v[182:185], v[18:25], v[34:41], v[182:185]
	v_mfma_f32_16x16x128_f8f6f4 v[178:181], v[26:33], v[34:41], v[178:181]
	v_mfma_f32_16x16x128_f8f6f4 v[166:169], v[18:25], v[42:49], v[166:169]
	v_mfma_f32_16x16x128_f8f6f4 v[162:165], v[26:33], v[42:49], v[162:165]
	v_mfma_f32_16x16x128_f8f6f4 v[150:153], v[18:25], v[50:57], v[150:153]
	v_mfma_f32_16x16x128_f8f6f4 v[146:149], v[26:33], v[50:57], v[146:149]
	v_mfma_f32_16x16x128_f8f6f4 v[134:137], v[18:25], v[58:65], v[134:137]
	v_mfma_f32_16x16x128_f8f6f4 v[130:133], v[26:33], v[58:65], v[130:133]
	s_setprio 0
	s_waitcnt vmcnt(8)
	s_barrier
	s_mov_b32 m0, s49
	ds_read_b128 v[34:37], v226 offset:49152
	ds_read_b128 v[38:41], v226 offset:50176
	ds_read_b128 v[42:45], v226 offset:51200
	ds_read_b128 v[46:49], v226 offset:52224
	ds_read_b128 v[50:53], v226 offset:53248
	ds_read_b128 v[54:57], v226 offset:54272
	ds_read_b128 v[58:61], v226 offset:55296
	ds_read_b128 v[62:65], v226 offset:56320
	s_add_u32 s98, s26, 0x80
	s_addc_u32 s99, s27, 0
	global_load_lds_dwordx4 v196, s[98:99]
	s_mov_b32 m0, s50
	s_nop 0
	global_load_lds_dwordx4 v200, s[98:99]
	s_mov_b32 m0, s54
	s_add_u32 s100, s70, 0x80
	s_addc_u32 s101, s71, 0
	global_load_lds_dwordx4 v196, s[100:101]
	s_mov_b32 m0, s55
	s_nop 0
	global_load_lds_dwordx4 v200, s[100:101]
	s_mov_b32 m0, s51
	s_add_u32 s98, s28, 0x100
	s_addc_u32 s99, s29, 0
	global_load_lds_dwordx4 v194, s[98:99]
	s_mov_b32 m0, s52
	s_nop 0
	global_load_lds_dwordx4 v198, s[98:99]
	s_waitcnt lgkmcnt(0)
	s_barrier
	s_setprio 1
	s_waitcnt lgkmcnt(0)
	v_mfma_f32_16x16x128_f8f6f4 v[126:129], v[2:9], v[34:41], v[126:129]
	v_mfma_f32_16x16x128_f8f6f4 v[122:125], v[10:17], v[34:41], v[122:125]
	v_mfma_f32_16x16x128_f8f6f4 v[110:113], v[2:9], v[42:49], v[110:113]
	v_mfma_f32_16x16x128_f8f6f4 v[106:109], v[10:17], v[42:49], v[106:109]
	v_mfma_f32_16x16x128_f8f6f4 v[94:97], v[2:9], v[50:57], v[94:97]
	v_mfma_f32_16x16x128_f8f6f4 v[90:93], v[10:17], v[50:57], v[90:93]
	v_mfma_f32_16x16x128_f8f6f4 v[78:81], v[2:9], v[58:65], v[78:81]
	v_mfma_f32_16x16x128_f8f6f4 v[74:77], v[10:17], v[58:65], v[74:77]
	s_setprio 0
	s_setprio 1
	v_mfma_f32_16x16x128_f8f6f4 v[118:121], v[18:25], v[34:41], v[118:121]
	v_mfma_f32_16x16x128_f8f6f4 v[114:117], v[26:33], v[34:41], v[114:117]
	v_mfma_f32_16x16x128_f8f6f4 v[102:105], v[18:25], v[42:49], v[102:105]
	v_mfma_f32_16x16x128_f8f6f4 v[98:101], v[26:33], v[42:49], v[98:101]
	v_mfma_f32_16x16x128_f8f6f4 v[86:89], v[18:25], v[50:57], v[86:89]
	v_mfma_f32_16x16x128_f8f6f4 v[82:85], v[26:33], v[50:57], v[82:85]
	v_mfma_f32_16x16x128_f8f6f4 v[70:73], v[18:25], v[58:65], v[70:73]
	v_mfma_f32_16x16x128_f8f6f4 v[66:69], v[26:33], v[58:65], v[66:69]
	s_setprio 0
	s_waitcnt vmcnt(8)
	s_barrier
	s_add_i32 s69, s69, 2
	s_add_u32 s6, s6, 0x200
	s_addc_u32 s7, s7, 0
	s_add_u32 s67, s67, 0x100
	s_addc_u32 s68, s68, 0
	s_cmp_gt_u32 s69, 13
	s_cbranch_scc1 .LBB0_2232

.LBB0_2409:
	s_waitcnt lgkmcnt(0)
	s_barrier
	s_setprio 1
	s_waitcnt lgkmcnt(0)
	v_mfma_f32_16x16x128_f8f6f4 v[126:129], v[26:33], v[58:65], v[126:129]
	v_mfma_f32_16x16x128_f8f6f4 v[122:125], v[18:25], v[58:65], v[122:125]
	v_mfma_f32_16x16x128_f8f6f4 v[114:117], v[26:33], v[50:57], v[114:117]
	v_mfma_f32_16x16x128_f8f6f4 v[106:109], v[18:25], v[50:57], v[106:109]
	v_mfma_f32_16x16x128_f8f6f4 v[98:101], v[26:33], v[42:49], v[98:101]
	v_mfma_f32_16x16x128_f8f6f4 v[90:93], v[18:25], v[42:49], v[90:93]
	v_mfma_f32_16x16x128_f8f6f4 v[82:85], v[26:33], v[34:41], v[82:85]
	v_mfma_f32_16x16x128_f8f6f4 v[74:77], v[18:25], v[34:41], v[74:77]
	s_setprio 0
	s_setprio 1
	v_mfma_f32_16x16x128_f8f6f4 v[118:121], v[10:17], v[58:65], v[118:121]
	v_mfma_f32_16x16x128_f8f6f4 v[110:113], v[2:9], v[58:65], v[110:113]
	v_mfma_f32_16x16x128_f8f6f4 v[102:105], v[10:17], v[50:57], v[102:105]
	v_mfma_f32_16x16x128_f8f6f4 v[94:97], v[2:9], v[50:57], v[94:97]
	v_mfma_f32_16x16x128_f8f6f4 v[86:89], v[10:17], v[42:49], v[86:89]
	v_mfma_f32_16x16x128_f8f6f4 v[78:81], v[2:9], v[42:49], v[78:81]
	v_mfma_f32_16x16x128_f8f6f4 v[70:73], v[10:17], v[34:41], v[70:73]
	v_mfma_f32_16x16x128_f8f6f4 v[66:69], v[2:9], v[34:41], v[66:69]
	s_setprio 0
	s_barrier
	v_add_u32_e32 v14, s57, v222
	v_add_u32_e32 v30, s62, v222
	ds_read_b128 v[2:5], v14
	ds_read_b128 v[6:9], v14 offset:1024
	ds_read_b128 v[10:13], v14 offset:2048
	ds_read_b128 v[14:17], v14 offset:3072
	ds_read_b128 v[18:21], v30
	ds_read_b128 v[22:25], v30 offset:1024
	ds_read_b128 v[26:29], v30 offset:2048
	ds_read_b128 v[30:33], v30 offset:3072
	s_add_u32 s100, s40, 0x40000
	s_addc_u32 s101, s41, 0
	s_mov_b32 m0, s55
	ds_read_b128 v[34:37], v226 offset:32768
	ds_read_b128 v[38:41], v226 offset:33792
	ds_read_b128 v[42:45], v226 offset:34816
	ds_read_b128 v[46:49], v226 offset:35840
	ds_read_b128 v[50:53], v226 offset:36864
	ds_read_b128 v[54:57], v226 offset:37888
	ds_read_b128 v[58:61], v226 offset:38912
	ds_read_b128 v[62:65], v226 offset:39936
	global_load_lds_dwordx4 v194, s[100:101]
	s_mov_b32 m0, s56
	s_nop 0
	global_load_lds_dwordx4 v198, s[100:101]
	s_waitcnt lgkmcnt(0)
	s_barrier
	s_setprio 1
	s_waitcnt lgkmcnt(0)
	v_mfma_f32_16x16x128_f8f6f4 v[190:193], v[2:9], v[34:41], v[190:193]
	v_mfma_f32_16x16x128_f8f6f4 v[186:189], v[10:17], v[34:41], v[186:189]
	v_mfma_f32_16x16x128_f8f6f4 v[178:181], v[2:9], v[42:49], v[178:181]
	v_mfma_f32_16x16x128_f8f6f4 v[170:173], v[10:17], v[42:49], v[170:173]
	v_mfma_f32_16x16x128_f8f6f4 v[162:165], v[2:9], v[50:57], v[162:165]
	v_mfma_f32_16x16x128_f8f6f4 v[154:157], v[10:17], v[50:57], v[154:157]
	v_mfma_f32_16x16x128_f8f6f4 v[146:149], v[2:9], v[58:65], v[146:149]
	v_mfma_f32_16x16x128_f8f6f4 v[138:141], v[10:17], v[58:65], v[138:141]
	s_setprio 0
	s_setprio 1
	v_mfma_f32_16x16x128_f8f6f4 v[182:185], v[18:25], v[34:41], v[182:185]
	v_mfma_f32_16x16x128_f8f6f4 v[174:177], v[26:33], v[34:41], v[174:177]
	v_mfma_f32_16x16x128_f8f6f4 v[166:169], v[18:25], v[42:49], v[166:169]
	v_mfma_f32_16x16x128_f8f6f4 v[158:161], v[26:33], v[42:49], v[158:161]
	v_mfma_f32_16x16x128_f8f6f4 v[150:153], v[18:25], v[50:57], v[150:153]
	v_mfma_f32_16x16x128_f8f6f4 v[142:145], v[26:33], v[50:57], v[142:145]
	v_mfma_f32_16x16x128_f8f6f4 v[134:137], v[18:25], v[58:65], v[134:137]
	v_mfma_f32_16x16x128_f8f6f4 v[130:133], v[26:33], v[58:65], v[130:133]
	s_setprio 0
	s_waitcnt vmcnt(8)
	s_barrier
	s_mov_b32 m0, s58
	ds_read_b128 v[34:37], v226 offset:49152
	ds_read_b128 v[38:41], v226 offset:50176
	ds_read_b128 v[42:45], v226 offset:51200
	ds_read_b128 v[46:49], v226 offset:52224
	ds_read_b128 v[50:53], v226 offset:53248
	ds_read_b128 v[54:57], v226 offset:54272
	ds_read_b128 v[58:61], v226 offset:55296
	ds_read_b128 v[62:65], v226 offset:56320
	s_add_u32 s98, s38, 0x80
	s_addc_u32 s99, s39, 0
	global_load_lds_dwordx4 v196, s[98:99]
	s_mov_b32 m0, s59
	s_nop 0
	global_load_lds_dwordx4 v200, s[98:99]
	s_mov_b32 m0, s63
	s_add_u32 s100, s78, 0x80
	s_addc_u32 s101, s79, 0
	global_load_lds_dwordx4 v196, s[100:101]
	s_mov_b32 m0, s64
	s_nop 0
	global_load_lds_dwordx4 v200, s[100:101]
	s_mov_b32 m0, s60
	s_add_u32 s98, s40, 0x80
	s_addc_u32 s99, s41, 0
	global_load_lds_dwordx4 v194, s[98:99]
	s_mov_b32 m0, s61
	s_nop 0
	global_load_lds_dwordx4 v198, s[98:99]
	s_waitcnt lgkmcnt(0)
	s_barrier
	s_setprio 1
	s_waitcnt lgkmcnt(0)
	v_mfma_f32_16x16x128_f8f6f4 v[126:129], v[2:9], v[34:41], v[126:129]
	v_mfma_f32_16x16x128_f8f6f4 v[122:125], v[10:17], v[34:41], v[122:125]
	v_mfma_f32_16x16x128_f8f6f4 v[114:117], v[2:9], v[42:49], v[114:117]
	v_mfma_f32_16x16x128_f8f6f4 v[106:109], v[10:17], v[42:49], v[106:109]
	v_mfma_f32_16x16x128_f8f6f4 v[98:101], v[2:9], v[50:57], v[98:101]
	v_mfma_f32_16x16x128_f8f6f4 v[90:93], v[10:17], v[50:57], v[90:93]
	v_mfma_f32_16x16x128_f8f6f4 v[82:85], v[2:9], v[58:65], v[82:85]
	v_mfma_f32_16x16x128_f8f6f4 v[74:77], v[10:17], v[58:65], v[74:77]
	s_setprio 0
	s_setprio 1
	v_mfma_f32_16x16x128_f8f6f4 v[118:121], v[18:25], v[34:41], v[118:121]
	v_mfma_f32_16x16x128_f8f6f4 v[110:113], v[26:33], v[34:41], v[110:113]
	v_mfma_f32_16x16x128_f8f6f4 v[102:105], v[18:25], v[42:49], v[102:105]
	v_mfma_f32_16x16x128_f8f6f4 v[94:97], v[26:33], v[42:49], v[94:97]
	v_mfma_f32_16x16x128_f8f6f4 v[86:89], v[18:25], v[50:57], v[86:89]
	v_mfma_f32_16x16x128_f8f6f4 v[78:81], v[26:33], v[50:57], v[78:81]
	v_mfma_f32_16x16x128_f8f6f4 v[70:73], v[18:25], v[58:65], v[70:73]
	v_mfma_f32_16x16x128_f8f6f4 v[66:69], v[26:33], v[58:65], v[66:69]
	s_setprio 0
	s_waitcnt vmcnt(8)
	s_barrier
	s_add_i32 s76, s76, 2
	s_add_u32 s36, s36, 0x100
	s_addc_u32 s37, s37, 0
	s_cmp_gt_u32 s76, 13
	s_cbranch_scc1 .LBB0_2417
.LBB0_2410:
	s_cmp_eq_u32 s36, 0
	s_cselect_b64 s[38:39], -1, 0
	s_and_b64 s[38:39], s[34:35], s[38:39]
	s_and_b32 s38, s38, 1
	ds_read_b128 v[26:29], v224
	ds_read_b128 v[30:33], v224 offset:1024
	ds_read_b128 v[18:21], v224 offset:2048
	ds_read_b128 v[22:25], v224 offset:3072
	ds_read_b128 v[10:13], v225
	ds_read_b128 v[14:17], v225 offset:1024
	ds_read_b128 v[2:5], v225 offset:2048
	ds_read_b128 v[6:9], v225 offset:3072
	s_add_u32 s98, s30, s36
	s_addc_u32 s99, s31, s37
	s_add_i32 m0, s53, 0xc000
	ds_read_b128 v[58:61], v226
	ds_read_b128 v[62:65], v226 offset:1024
	ds_read_b128 v[50:53], v226 offset:2048
	ds_read_b128 v[54:57], v226 offset:3072
	ds_read_b128 v[42:45], v226 offset:4096
	ds_read_b128 v[46:49], v226 offset:5120
	ds_read_b128 v[34:37], v226 offset:6144
	ds_read_b128 v[38:41], v226 offset:7168
	global_load_lds_dwordx4 v204, s[98:99]
	s_add_i32 m0, s53, 0xe000
	s_cmp_lg_u32 s38, 0
	global_load_lds_dwordx4 v202, s[98:99]
	s_cselect_b64 s[42:43], -1, 0
	s_cmp_eq_u32 s38, 0
	s_cbranch_scc1 .LBB0_2415
	s_waitcnt vmcnt(24)
	s_cbranch_execnz .LBB0_2413

.LBB0_2741:
	s_waitcnt lgkmcnt(0)
	s_barrier
	s_setprio 1
	s_waitcnt lgkmcnt(0)
	v_mfma_f32_16x16x32_bf16 v[62:65], v[146:149], v[186:189], v[62:65]
	v_mfma_f32_16x16x32_bf16 v[58:61], v[154:157], v[186:189], v[58:61]
	v_mfma_f32_16x16x32_bf16 v[54:57], v[146:149], v[178:181], v[54:57]
	v_mfma_f32_16x16x32_bf16 v[46:49], v[154:157], v[178:181], v[46:49]
	v_mfma_f32_16x16x32_bf16 v[38:41], v[146:149], v[170:173], v[38:41]
	v_mfma_f32_16x16x32_bf16 v[30:33], v[154:157], v[170:173], v[30:33]
	v_mfma_f32_16x16x32_bf16 v[22:25], v[146:149], v[162:165], v[22:25]
	v_mfma_f32_16x16x32_bf16 v[14:17], v[154:157], v[162:165], v[14:17]
	v_mfma_f32_16x16x32_bf16 v[62:65], v[150:153], v[190:193], v[62:65]
	v_mfma_f32_16x16x32_bf16 v[58:61], v[158:161], v[190:193], v[58:61]
	v_mfma_f32_16x16x32_bf16 v[54:57], v[150:153], v[182:185], v[54:57]
	v_mfma_f32_16x16x32_bf16 v[46:49], v[158:161], v[182:185], v[46:49]
	v_mfma_f32_16x16x32_bf16 v[38:41], v[150:153], v[174:177], v[38:41]
	v_mfma_f32_16x16x32_bf16 v[30:33], v[158:161], v[174:177], v[30:33]
	v_mfma_f32_16x16x32_bf16 v[22:25], v[150:153], v[166:169], v[22:25]
	v_mfma_f32_16x16x32_bf16 v[14:17], v[158:161], v[166:169], v[14:17]
	s_setprio 0
	s_setprio 1
	v_mfma_f32_16x16x32_bf16 v[50:53], v[130:133], v[186:189], v[50:53]
	v_mfma_f32_16x16x32_bf16 v[42:45], v[138:141], v[186:189], v[42:45]
	v_mfma_f32_16x16x32_bf16 v[34:37], v[130:133], v[178:181], v[34:37]
	v_mfma_f32_16x16x32_bf16 v[26:29], v[138:141], v[178:181], v[26:29]
	v_mfma_f32_16x16x32_bf16 v[18:21], v[130:133], v[170:173], v[18:21]
	v_mfma_f32_16x16x32_bf16 v[10:13], v[138:141], v[170:173], v[10:13]
	v_mfma_f32_16x16x32_bf16 v[6:9], v[130:133], v[162:165], v[6:9]
	v_mfma_f32_16x16x32_bf16 v[2:5], v[138:141], v[162:165], v[2:5]
	v_mfma_f32_16x16x32_bf16 v[50:53], v[134:137], v[190:193], v[50:53]
	v_mfma_f32_16x16x32_bf16 v[42:45], v[142:145], v[190:193], v[42:45]
	v_mfma_f32_16x16x32_bf16 v[34:37], v[134:137], v[182:185], v[34:37]
	v_mfma_f32_16x16x32_bf16 v[26:29], v[142:145], v[182:185], v[26:29]
	v_mfma_f32_16x16x32_bf16 v[18:21], v[134:137], v[174:177], v[18:21]
	v_mfma_f32_16x16x32_bf16 v[10:13], v[142:145], v[174:177], v[10:13]
	v_mfma_f32_16x16x32_bf16 v[6:9], v[134:137], v[166:169], v[6:9]
	v_mfma_f32_16x16x32_bf16 v[2:5], v[142:145], v[166:169], v[2:5]
	s_setprio 0
	s_barrier
	v_add_u32_e32 v142, s48, v222
	v_add_u32_e32 v158, s53, v222
	ds_read_b128 v[130:133], v142
	ds_read_b128 v[134:137], v142 offset:1024
	ds_read_b128 v[138:141], v142 offset:2048
	ds_read_b128 v[142:145], v142 offset:3072
	ds_read_b128 v[146:149], v158
	ds_read_b128 v[150:153], v158 offset:1024
	ds_read_b128 v[154:157], v158 offset:2048
	ds_read_b128 v[158:161], v158 offset:3072
	s_add_u32 s100, s30, 0x160000
	s_addc_u32 s101, s31, 0
	s_mov_b32 m0, s46
	ds_read_b128 v[162:165], v226 offset:32768
	ds_read_b128 v[166:169], v226 offset:33792
	ds_read_b128 v[170:173], v226 offset:34816
	ds_read_b128 v[174:177], v226 offset:35840
	ds_read_b128 v[178:181], v226 offset:36864
	ds_read_b128 v[182:185], v226 offset:37888
	ds_read_b128 v[186:189], v226 offset:38912
	ds_read_b128 v[190:193], v226 offset:39936
	global_load_lds_dwordx4 v194, s[100:101]
	s_mov_b32 m0, s47
	s_nop 0
	global_load_lds_dwordx4 v198, s[100:101]
	s_waitcnt lgkmcnt(0)
	s_barrier
	s_setprio 1
	s_waitcnt lgkmcnt(0)
	v_mfma_f32_16x16x32_bf16 v[126:129], v[130:133], v[162:165], v[126:129]
	v_mfma_f32_16x16x32_bf16 v[122:125], v[138:141], v[162:165], v[122:125]
	v_mfma_f32_16x16x32_bf16 v[118:121], v[130:133], v[170:173], v[118:121]
	v_mfma_f32_16x16x32_bf16 v[110:113], v[138:141], v[170:173], v[110:113]
	v_mfma_f32_16x16x32_bf16 v[102:105], v[130:133], v[178:181], v[102:105]
	v_mfma_f32_16x16x32_bf16 v[94:97], v[138:141], v[178:181], v[94:97]
	v_mfma_f32_16x16x32_bf16 v[86:89], v[130:133], v[186:189], v[86:89]
	v_mfma_f32_16x16x32_bf16 v[78:81], v[138:141], v[186:189], v[78:81]
	v_mfma_f32_16x16x32_bf16 v[126:129], v[134:137], v[166:169], v[126:129]
	v_mfma_f32_16x16x32_bf16 v[122:125], v[142:145], v[166:169], v[122:125]
	v_mfma_f32_16x16x32_bf16 v[118:121], v[134:137], v[174:177], v[118:121]
	v_mfma_f32_16x16x32_bf16 v[110:113], v[142:145], v[174:177], v[110:113]
	v_mfma_f32_16x16x32_bf16 v[102:105], v[134:137], v[182:185], v[102:105]
	v_mfma_f32_16x16x32_bf16 v[94:97], v[142:145], v[182:185], v[94:97]
	v_mfma_f32_16x16x32_bf16 v[86:89], v[134:137], v[190:193], v[86:89]
	v_mfma_f32_16x16x32_bf16 v[78:81], v[142:145], v[190:193], v[78:81]
	s_setprio 0
	s_setprio 1
	v_mfma_f32_16x16x32_bf16 v[114:117], v[146:149], v[162:165], v[114:117]
	v_mfma_f32_16x16x32_bf16 v[106:109], v[154:157], v[162:165], v[106:109]
	v_mfma_f32_16x16x32_bf16 v[98:101], v[146:149], v[170:173], v[98:101]
	v_mfma_f32_16x16x32_bf16 v[90:93], v[154:157], v[170:173], v[90:93]
	v_mfma_f32_16x16x32_bf16 v[82:85], v[146:149], v[178:181], v[82:85]
	v_mfma_f32_16x16x32_bf16 v[74:77], v[154:157], v[178:181], v[74:77]
	v_mfma_f32_16x16x32_bf16 v[70:73], v[146:149], v[186:189], v[70:73]
	v_mfma_f32_16x16x32_bf16 v[66:69], v[154:157], v[186:189], v[66:69]
	v_mfma_f32_16x16x32_bf16 v[114:117], v[150:153], v[166:169], v[114:117]
	v_mfma_f32_16x16x32_bf16 v[106:109], v[158:161], v[166:169], v[106:109]
	v_mfma_f32_16x16x32_bf16 v[98:101], v[150:153], v[174:177], v[98:101]
	v_mfma_f32_16x16x32_bf16 v[90:93], v[158:161], v[174:177], v[90:93]
	v_mfma_f32_16x16x32_bf16 v[82:85], v[150:153], v[182:185], v[82:85]
	v_mfma_f32_16x16x32_bf16 v[74:77], v[158:161], v[182:185], v[74:77]
	v_mfma_f32_16x16x32_bf16 v[70:73], v[150:153], v[190:193], v[70:73]
	v_mfma_f32_16x16x32_bf16 v[66:69], v[158:161], v[190:193], v[66:69]
	s_setprio 0
	s_waitcnt vmcnt(8)
	s_barrier
	s_mov_b32 m0, s49
	ds_read_b128 v[162:165], v226 offset:49152
	ds_read_b128 v[166:169], v226 offset:50176
	ds_read_b128 v[170:173], v226 offset:51200
	ds_read_b128 v[174:177], v226 offset:52224
	ds_read_b128 v[178:181], v226 offset:53248
	ds_read_b128 v[182:185], v226 offset:54272
	ds_read_b128 v[186:189], v226 offset:55296
	ds_read_b128 v[190:193], v226 offset:56320
	s_add_u32 s98, s28, 0x80
	s_addc_u32 s99, s29, 0
	global_load_lds_dwordx4 v196, s[98:99]
	s_mov_b32 m0, s50
	s_nop 0
	global_load_lds_dwordx4 v200, s[98:99]
	s_mov_b32 m0, s54
	s_add_u32 s100, s70, 0x80
	s_addc_u32 s101, s71, 0
	global_load_lds_dwordx4 v196, s[100:101]
	s_mov_b32 m0, s55
	s_nop 0
	global_load_lds_dwordx4 v200, s[100:101]
	s_mov_b32 m0, s51
	s_add_u32 s98, s30, 0x80
	s_addc_u32 s99, s31, 0
	global_load_lds_dwordx4 v194, s[98:99]
	s_mov_b32 m0, s52
	s_nop 0
	global_load_lds_dwordx4 v198, s[98:99]
	s_waitcnt lgkmcnt(0)
	s_barrier
	s_setprio 1
	s_waitcnt lgkmcnt(0)
	v_mfma_f32_16x16x32_bf16 v[62:65], v[130:133], v[162:165], v[62:65]
	v_mfma_f32_16x16x32_bf16 v[58:61], v[138:141], v[162:165], v[58:61]
	v_mfma_f32_16x16x32_bf16 v[54:57], v[130:133], v[170:173], v[54:57]
	v_mfma_f32_16x16x32_bf16 v[46:49], v[138:141], v[170:173], v[46:49]
	v_mfma_f32_16x16x32_bf16 v[38:41], v[130:133], v[178:181], v[38:41]
	v_mfma_f32_16x16x32_bf16 v[30:33], v[138:141], v[178:181], v[30:33]
	v_mfma_f32_16x16x32_bf16 v[22:25], v[130:133], v[186:189], v[22:25]
	v_mfma_f32_16x16x32_bf16 v[14:17], v[138:141], v[186:189], v[14:17]
	v_mfma_f32_16x16x32_bf16 v[62:65], v[134:137], v[166:169], v[62:65]
	v_mfma_f32_16x16x32_bf16 v[58:61], v[142:145], v[166:169], v[58:61]
	v_mfma_f32_16x16x32_bf16 v[54:57], v[134:137], v[174:177], v[54:57]
	v_mfma_f32_16x16x32_bf16 v[46:49], v[142:145], v[174:177], v[46:49]
	v_mfma_f32_16x16x32_bf16 v[38:41], v[134:137], v[182:185], v[38:41]
	v_mfma_f32_16x16x32_bf16 v[30:33], v[142:145], v[182:185], v[30:33]
	v_mfma_f32_16x16x32_bf16 v[22:25], v[134:137], v[190:193], v[22:25]
	v_mfma_f32_16x16x32_bf16 v[14:17], v[142:145], v[190:193], v[14:17]
	s_setprio 0
	s_setprio 1
	v_mfma_f32_16x16x32_bf16 v[50:53], v[146:149], v[162:165], v[50:53]
	v_mfma_f32_16x16x32_bf16 v[42:45], v[154:157], v[162:165], v[42:45]
	v_mfma_f32_16x16x32_bf16 v[34:37], v[146:149], v[170:173], v[34:37]
	v_mfma_f32_16x16x32_bf16 v[26:29], v[154:157], v[170:173], v[26:29]
	v_mfma_f32_16x16x32_bf16 v[18:21], v[146:149], v[178:181], v[18:21]
	v_mfma_f32_16x16x32_bf16 v[10:13], v[154:157], v[178:181], v[10:13]
	v_mfma_f32_16x16x32_bf16 v[6:9], v[146:149], v[186:189], v[6:9]
	v_mfma_f32_16x16x32_bf16 v[2:5], v[154:157], v[186:189], v[2:5]
	v_mfma_f32_16x16x32_bf16 v[50:53], v[150:153], v[166:169], v[50:53]
	v_mfma_f32_16x16x32_bf16 v[42:45], v[158:161], v[166:169], v[42:45]
	v_mfma_f32_16x16x32_bf16 v[34:37], v[150:153], v[174:177], v[34:37]
	v_mfma_f32_16x16x32_bf16 v[26:29], v[158:161], v[174:177], v[26:29]
	v_mfma_f32_16x16x32_bf16 v[18:21], v[150:153], v[182:185], v[18:21]
	v_mfma_f32_16x16x32_bf16 v[10:13], v[158:161], v[182:185], v[10:13]
	v_mfma_f32_16x16x32_bf16 v[6:9], v[150:153], v[190:193], v[6:9]
	v_mfma_f32_16x16x32_bf16 v[2:5], v[158:161], v[190:193], v[2:5]
	s_setprio 0
	s_waitcnt vmcnt(8)
	s_barrier
	s_add_i32 s69, s69, 2
	s_add_u32 s26, s26, 0x100
	s_addc_u32 s27, s27, 0
	s_cmpk_gt_u32 s69, 0x55
	s_cbranch_scc1 .LBB0_2749
.LBB0_2742:
	s_cmp_eq_u32 s26, 0
	s_cselect_b64 s[28:29], -1, 0
	s_and_b64 s[28:29], s[24:25], s[28:29]
	s_and_b32 s28, s28, 1
	ds_read_b128 v[146:149], v224
	ds_read_b128 v[150:153], v224 offset:1024
	ds_read_b128 v[154:157], v224 offset:2048
	ds_read_b128 v[158:161], v224 offset:3072
	ds_read_b128 v[130:133], v225
	ds_read_b128 v[134:137], v225 offset:1024
	ds_read_b128 v[138:141], v225 offset:2048
	ds_read_b128 v[142:145], v225 offset:3072
	s_add_u32 s98, s22, s26
	s_addc_u32 s99, s23, s27
	s_add_i32 m0, s44, 0xc000
	ds_read_b128 v[186:189], v226
	ds_read_b128 v[190:193], v226 offset:1024
	ds_read_b128 v[178:181], v226 offset:2048
	ds_read_b128 v[182:185], v226 offset:3072
	ds_read_b128 v[170:173], v226 offset:4096
	ds_read_b128 v[174:177], v226 offset:5120
	ds_read_b128 v[162:165], v226 offset:6144
	ds_read_b128 v[166:169], v226 offset:7168
	global_load_lds_dwordx4 v204, s[98:99]
	s_add_i32 m0, s44, 0xe000
	s_cmp_lg_u32 s28, 0
	global_load_lds_dwordx4 v202, s[98:99]
	s_cselect_b64 s[34:35], -1, 0
	s_cmp_eq_u32 s28, 0
	s_cbranch_scc1 .LBB0_2747
	s_waitcnt vmcnt(24)
	s_cbranch_execnz .LBB0_2745
